# comb12 + grid-barrier spin loops poll without the s_sleep between polls
# baseline (speedup 1.0000x reference)
; __global__ void __launch_bounds__(NTHR, 2) fwd_megakernel(Args args) {
;     ...
;     if (args.coop == 2) grid.sync();
.LBB0_16:
	s_nop 0
	global_load_dword v2, v0, s[4:5] offset:32 sc1
	s_waitcnt vmcnt(0)
	v_and_b32_e32 v2, 0xffff0000, v2
	v_cmp_ne_u32_e32 vcc, v2, v1
	s_or_b64 s[6:7], vcc, s[6:7]
	s_andn2_b64 exec, exec, s[6:7]
	s_cbranch_execnz .LBB0_16

; __device__ __forceinline__ unsigned xb_ld(unsigned* p)              { return __hip_atomic_load(p, __ATOMIC_RELAXED, __HIP_MEMORY_SCOPE_AGENT); }
; __device__ __forceinline__ void xcd_barrier_complete(unsigned* bar, unsigned x, unsigned& nloc, unsigned& nx) {
;     ...
;     for (;;) {
;         sum = 0u; cnt = 0u; mine = 0u;
; #pragma unroll
;         for (unsigned j = 0; j < 16; ++j) { const unsigned c = xb_ld(&bar[XB_XCNT(j)]); sum += c; cnt += (c > 0u) ? 1u : 0u; mine = (j == x) ? c : mine; }
;         if (sum == G) break;
;         __builtin_amdgcn_s_sleep(1);
;         if ((++sp & 255u) == 0u) { if (xb_ld(&bar[XB_TMO])) break; if (sp > XB_SPIN_CAP) { atomicAdd(&bar[XB_TMO], 1u); break; } }
;     }
.LBB0_178:
	global_load_dword v15, v16, s[20:21] sc1
	global_load_dword v0, v16, s[22:23] sc1
	global_load_dword v1, v16, s[24:25] sc1
	global_load_dword v2, v16, s[26:27] sc1
	global_load_dword v3, v16, s[28:29] sc1
	global_load_dword v4, v16, s[30:31] sc1
	global_load_dword v5, v16, s[36:37] sc1
	global_load_dword v6, v16, s[38:39] sc1
	global_load_dword v7, v16, s[40:41] sc1
	global_load_dword v8, v16, s[42:43] sc1
	global_load_dword v9, v16, s[64:65] sc1
	global_load_dword v10, v16, s[66:67] sc1
	global_load_dword v11, v16, s[68:69] sc1
	global_load_dword v12, v16, s[70:71] sc1
	global_load_dword v13, v16, s[72:73] sc1
	global_load_dword v14, v16, s[74:75] sc1
	s_mov_b64 s[76:77], -1
	s_mov_b64 s[78:79], -1
	s_waitcnt vmcnt(14)
	v_add_u32_e32 v17, v0, v15
	s_waitcnt vmcnt(13)
	v_add_u32_e32 v17, v17, v1
	s_waitcnt vmcnt(12)
	v_add_u32_e32 v17, v17, v2
	s_waitcnt vmcnt(11)
	v_add_u32_e32 v17, v17, v3
	s_waitcnt vmcnt(10)
	v_add_u32_e32 v17, v17, v4
	s_waitcnt vmcnt(9)
	v_add_u32_e32 v17, v17, v5
	s_waitcnt vmcnt(8)
	v_add_u32_e32 v17, v17, v6
	s_waitcnt vmcnt(7)
	v_add_u32_e32 v17, v17, v7
	s_waitcnt vmcnt(6)
	v_add_u32_e32 v17, v17, v8
	s_waitcnt vmcnt(5)
	v_add_u32_e32 v17, v17, v9
	s_waitcnt vmcnt(4)
	v_add_u32_e32 v17, v17, v10
	s_waitcnt vmcnt(3)
	v_add_u32_e32 v17, v17, v11
	s_waitcnt vmcnt(2)
	v_add_u32_e32 v17, v17, v12
	s_waitcnt vmcnt(1)
	v_add_u32_e32 v17, v17, v13
	s_waitcnt vmcnt(0)
	v_add_u32_e32 v17, v17, v14
	v_cmp_eq_u32_e32 vcc, s11, v17
	s_cbranch_vccnz .LBB0_177
	s_and_b32 s18, s44, 0xff
	s_cmp_eq_u32 s18, 0
	s_mov_b64 s[80:81], -1
	s_nop 0
	s_cbranch_scc1 .LBB0_182
	s_and_b64 vcc, exec, s[80:81]
	s_cbranch_vccz .LBB0_177

; __device__ __forceinline__ unsigned xb_ld(unsigned* p)              { return __hip_atomic_load(p, __ATOMIC_RELAXED, __HIP_MEMORY_SCOPE_AGENT); }
; __device__ __forceinline__ unsigned xb_add(unsigned* p, unsigned v) { return __hip_atomic_fetch_add(p, v, __ATOMIC_RELAXED, __HIP_MEMORY_SCOPE_AGENT); }
; #define XB_SPIN(cond, bar) do { unsigned _sp = 0; while (cond) { __builtin_amdgcn_s_sleep(1); \
;     if ((++_sp & 255u) == 0u) { if (xb_ld(&(bar)[XB_TMO])) break; if (_sp > XB_SPIN_CAP) { atomicAdd(&(bar)[XB_TMO], 1u); break; } } } } while (0)
; __device__ __forceinline__ void xcd_barrier(const XcdBarrier& b) {
;     ...
;             const unsigned og = xb_add(&bar[XB_TOP], 1u);
;             const unsigned tg = og / nx;
;             if (og + 1u == (tg + 1u) * nx) xb_add(&bar[XB_TOPGEN], 1u);
;             else XB_SPIN(xb_ld(&bar[XB_TOPGEN]) == tg, bar);
.LBB0_194:
	s_and_b32 s18, s11, 0xff
	s_mov_b64 s[36:37], -1
	s_cmp_lg_u32 s18, 0
	s_mov_b64 s[40:41], -1
	s_nop 0
	s_cbranch_scc0 .LBB0_197
	s_and_b64 vcc, exec, s[40:41]
	s_cbranch_vccz .LBB0_193

; __device__ __forceinline__ unsigned xb_ld(unsigned* p)              { return __hip_atomic_load(p, __ATOMIC_RELAXED, __HIP_MEMORY_SCOPE_AGENT); }
; #define XB_SPIN(cond, bar) do { unsigned _sp = 0; while (cond) { __builtin_amdgcn_s_sleep(1); \
;     if ((++_sp & 255u) == 0u) { if (xb_ld(&(bar)[XB_TMO])) break; if (_sp > XB_SPIN_CAP) { atomicAdd(&(bar)[XB_TMO], 1u); break; } } } } while (0)
; __device__ __forceinline__ void xcd_barrier(const XcdBarrier& b) {
;     ...
;         } else {
;             XB_SPIN(xb_ld(&bar[XB_XGEN(b.x)]) == gen, bar);
.LBB0_211:
	s_and_b32 s18, s11, 0xff
	s_cmp_lg_u32 s18, 0
	s_mov_b64 s[38:39], -1
	s_nop 0
	s_cbranch_scc0 .LBB0_214
	s_mov_b64 s[40:41], -1
	s_and_b64 vcc, exec, s[38:39]
	s_cbranch_vccz .LBB0_210

; __device__ __forceinline__ unsigned xb_ld(unsigned* p)              { return __hip_atomic_load(p, __ATOMIC_RELAXED, __HIP_MEMORY_SCOPE_AGENT); }
; __device__ __forceinline__ void xcd_barrier_complete(unsigned* bar, unsigned x, unsigned& nloc, unsigned& nx) {
;     ...
;     for (;;) {
;         sum = 0u; cnt = 0u; mine = 0u;
; #pragma unroll
;         for (unsigned j = 0; j < 16; ++j) { const unsigned c = xb_ld(&bar[XB_XCNT(j)]); sum += c; cnt += (c > 0u) ? 1u : 0u; mine = (j == x) ? c : mine; }
;         if (sum == G) break;
;         __builtin_amdgcn_s_sleep(1);
;         if ((++sp & 255u) == 0u) { if (xb_ld(&bar[XB_TMO])) break; if (sp > XB_SPIN_CAP) { atomicAdd(&bar[XB_TMO], 1u); break; } }
;     }
.LBB0_296:
	global_load_dword v15, v16, s[20:21] sc1
	global_load_dword v0, v16, s[22:23] sc1
	global_load_dword v1, v16, s[24:25] sc1
	global_load_dword v2, v16, s[26:27] sc1
	global_load_dword v3, v16, s[36:37] sc1
	global_load_dword v4, v16, s[38:39] sc1
	global_load_dword v5, v16, s[40:41] sc1
	global_load_dword v6, v16, s[42:43] sc1
	global_load_dword v7, v16, s[60:61] sc1
	global_load_dword v8, v16, s[62:63] sc1
	global_load_dword v9, v16, s[64:65] sc1
	global_load_dword v10, v16, s[66:67] sc1
	global_load_dword v11, v16, s[68:69] sc1
	global_load_dword v12, v16, s[70:71] sc1
	global_load_dword v13, v16, s[72:73] sc1
	global_load_dword v14, v16, s[74:75] sc1
	s_mov_b64 s[76:77], -1
	s_mov_b64 s[78:79], -1
	s_waitcnt vmcnt(14)
	v_add_u32_e32 v17, v0, v15
	s_waitcnt vmcnt(13)
	v_add_u32_e32 v17, v17, v1
	s_waitcnt vmcnt(12)
	v_add_u32_e32 v17, v17, v2
	s_waitcnt vmcnt(11)
	v_add_u32_e32 v17, v17, v3
	s_waitcnt vmcnt(10)
	v_add_u32_e32 v17, v17, v4
	s_waitcnt vmcnt(9)
	v_add_u32_e32 v17, v17, v5
	s_waitcnt vmcnt(8)
	v_add_u32_e32 v17, v17, v6
	s_waitcnt vmcnt(7)
	v_add_u32_e32 v17, v17, v7
	s_waitcnt vmcnt(6)
	v_add_u32_e32 v17, v17, v8
	s_waitcnt vmcnt(5)
	v_add_u32_e32 v17, v17, v9
	s_waitcnt vmcnt(4)
	v_add_u32_e32 v17, v17, v10
	s_waitcnt vmcnt(3)
	v_add_u32_e32 v17, v17, v11
	s_waitcnt vmcnt(2)
	v_add_u32_e32 v17, v17, v12
	s_waitcnt vmcnt(1)
	v_add_u32_e32 v17, v17, v13
	s_waitcnt vmcnt(0)
	v_add_u32_e32 v17, v17, v14
	v_cmp_eq_u32_e32 vcc, s11, v17
	s_cbranch_vccnz .LBB0_295
	s_and_b32 s18, s44, 0xff
	s_cmp_eq_u32 s18, 0
	s_mov_b64 s[80:81], -1
	s_nop 0
	s_cbranch_scc1 .LBB0_300
	s_and_b64 vcc, exec, s[80:81]
	s_cbranch_vccz .LBB0_295

; __device__ __forceinline__ unsigned xb_ld(unsigned* p)              { return __hip_atomic_load(p, __ATOMIC_RELAXED, __HIP_MEMORY_SCOPE_AGENT); }
; __device__ __forceinline__ unsigned xb_add(unsigned* p, unsigned v) { return __hip_atomic_fetch_add(p, v, __ATOMIC_RELAXED, __HIP_MEMORY_SCOPE_AGENT); }
; #define XB_SPIN(cond, bar) do { unsigned _sp = 0; while (cond) { __builtin_amdgcn_s_sleep(1); \
;     if ((++_sp & 255u) == 0u) { if (xb_ld(&(bar)[XB_TMO])) break; if (_sp > XB_SPIN_CAP) { atomicAdd(&(bar)[XB_TMO], 1u); break; } } } } while (0)
; __device__ __forceinline__ void xcd_barrier(const XcdBarrier& b) {
;     ...
;             const unsigned og = xb_add(&bar[XB_TOP], 1u);
;             const unsigned tg = og / nx;
;             if (og + 1u == (tg + 1u) * nx) xb_add(&bar[XB_TOPGEN], 1u);
;             else XB_SPIN(xb_ld(&bar[XB_TOPGEN]) == tg, bar);
.LBB0_312:
	s_and_b32 s18, s11, 0xff
	s_mov_b64 s[40:41], -1
	s_cmp_lg_u32 s18, 0
	s_mov_b64 s[60:61], -1
	s_nop 0
	s_cbranch_scc0 .LBB0_315
	s_and_b64 vcc, exec, s[60:61]
	s_cbranch_vccz .LBB0_311

; __device__ __forceinline__ unsigned xb_ld(unsigned* p)              { return __hip_atomic_load(p, __ATOMIC_RELAXED, __HIP_MEMORY_SCOPE_AGENT); }
; #define XB_SPIN(cond, bar) do { unsigned _sp = 0; while (cond) { __builtin_amdgcn_s_sleep(1); \
;     if ((++_sp & 255u) == 0u) { if (xb_ld(&(bar)[XB_TMO])) break; if (_sp > XB_SPIN_CAP) { atomicAdd(&(bar)[XB_TMO], 1u); break; } } } } while (0)
; __device__ __forceinline__ void xcd_barrier(const XcdBarrier& b) {
;     ...
;         } else {
;             XB_SPIN(xb_ld(&bar[XB_XGEN(b.x)]) == gen, bar);
.LBB0_329:
	s_and_b32 s18, s11, 0xff
	s_cmp_lg_u32 s18, 0
	s_mov_b64 s[42:43], -1
	s_nop 0
	s_cbranch_scc0 .LBB0_332
	s_mov_b64 s[60:61], -1
	s_and_b64 vcc, exec, s[42:43]
	s_cbranch_vccz .LBB0_328

; __device__ __forceinline__ unsigned xb_ld(unsigned* p)              { return __hip_atomic_load(p, __ATOMIC_RELAXED, __HIP_MEMORY_SCOPE_AGENT); }
; __device__ __forceinline__ void xcd_barrier_complete(unsigned* bar, unsigned x, unsigned& nloc, unsigned& nx) {
;     ...
;     for (;;) {
;         sum = 0u; cnt = 0u; mine = 0u;
; #pragma unroll
;         for (unsigned j = 0; j < 16; ++j) { const unsigned c = xb_ld(&bar[XB_XCNT(j)]); sum += c; cnt += (c > 0u) ? 1u : 0u; mine = (j == x) ? c : mine; }
;         if (sum == G) break;
;         __builtin_amdgcn_s_sleep(1);
;         if ((++sp & 255u) == 0u) { if (xb_ld(&bar[XB_TMO])) break; if (sp > XB_SPIN_CAP) { atomicAdd(&bar[XB_TMO], 1u); break; } }
;     }
.LBB0_389:
	global_load_dword v15, v16, s[20:21] sc1
	global_load_dword v0, v16, s[22:23] sc1
	global_load_dword v1, v16, s[24:25] sc1
	global_load_dword v2, v16, s[26:27] sc1
	global_load_dword v3, v16, s[36:37] sc1
	global_load_dword v4, v16, s[38:39] sc1
	global_load_dword v5, v16, s[40:41] sc1
	global_load_dword v6, v16, s[42:43] sc1
	global_load_dword v7, v16, s[58:59] sc1
	global_load_dword v8, v16, s[60:61] sc1
	global_load_dword v9, v16, s[62:63] sc1
	global_load_dword v10, v16, s[64:65] sc1
	global_load_dword v11, v16, s[66:67] sc1
	global_load_dword v12, v16, s[68:69] sc1
	global_load_dword v13, v16, s[70:71] sc1
	global_load_dword v14, v16, s[72:73] sc1
	s_mov_b64 s[74:75], -1
	s_mov_b64 s[76:77], -1
	s_waitcnt vmcnt(14)
	v_add_u32_e32 v17, v0, v15
	s_waitcnt vmcnt(13)
	v_add_u32_e32 v17, v17, v1
	s_waitcnt vmcnt(12)
	v_add_u32_e32 v17, v17, v2
	s_waitcnt vmcnt(11)
	v_add_u32_e32 v17, v17, v3
	s_waitcnt vmcnt(10)
	v_add_u32_e32 v17, v17, v4
	s_waitcnt vmcnt(9)
	v_add_u32_e32 v17, v17, v5
	s_waitcnt vmcnt(8)
	v_add_u32_e32 v17, v17, v6
	s_waitcnt vmcnt(7)
	v_add_u32_e32 v17, v17, v7
	s_waitcnt vmcnt(6)
	v_add_u32_e32 v17, v17, v8
	s_waitcnt vmcnt(5)
	v_add_u32_e32 v17, v17, v9
	s_waitcnt vmcnt(4)
	v_add_u32_e32 v17, v17, v10
	s_waitcnt vmcnt(3)
	v_add_u32_e32 v17, v17, v11
	s_waitcnt vmcnt(2)
	v_add_u32_e32 v17, v17, v12
	s_waitcnt vmcnt(1)
	v_add_u32_e32 v17, v17, v13
	s_waitcnt vmcnt(0)
	v_add_u32_e32 v17, v17, v14
	v_cmp_eq_u32_e32 vcc, s11, v17
	s_cbranch_vccnz .LBB0_388
	s_and_b32 s18, s44, 0xff
	s_cmp_eq_u32 s18, 0
	s_mov_b64 s[78:79], -1
	s_nop 0
	s_cbranch_scc1 .LBB0_393
	s_and_b64 vcc, exec, s[78:79]
	s_cbranch_vccz .LBB0_388

; __device__ __forceinline__ unsigned xb_ld(unsigned* p)              { return __hip_atomic_load(p, __ATOMIC_RELAXED, __HIP_MEMORY_SCOPE_AGENT); }
; __device__ __forceinline__ unsigned xb_add(unsigned* p, unsigned v) { return __hip_atomic_fetch_add(p, v, __ATOMIC_RELAXED, __HIP_MEMORY_SCOPE_AGENT); }
; #define XB_SPIN(cond, bar) do { unsigned _sp = 0; while (cond) { __builtin_amdgcn_s_sleep(1); \
;     if ((++_sp & 255u) == 0u) { if (xb_ld(&(bar)[XB_TMO])) break; if (_sp > XB_SPIN_CAP) { atomicAdd(&(bar)[XB_TMO], 1u); break; } } } } while (0)
; __device__ __forceinline__ void xcd_barrier(const XcdBarrier& b) {
;     ...
;             const unsigned og = xb_add(&bar[XB_TOP], 1u);
;             const unsigned tg = og / nx;
;             if (og + 1u == (tg + 1u) * nx) xb_add(&bar[XB_TOPGEN], 1u);
;             else XB_SPIN(xb_ld(&bar[XB_TOPGEN]) == tg, bar);
.LBB0_405:
	s_and_b32 s18, s11, 0xff
	s_mov_b64 s[40:41], -1
	s_cmp_lg_u32 s18, 0
	s_mov_b64 s[58:59], -1
	s_nop 0
	s_cbranch_scc0 .LBB0_408
	s_and_b64 vcc, exec, s[58:59]
	s_cbranch_vccz .LBB0_404

; __device__ __forceinline__ unsigned xb_ld(unsigned* p)              { return __hip_atomic_load(p, __ATOMIC_RELAXED, __HIP_MEMORY_SCOPE_AGENT); }
; #define XB_SPIN(cond, bar) do { unsigned _sp = 0; while (cond) { __builtin_amdgcn_s_sleep(1); \
;     if ((++_sp & 255u) == 0u) { if (xb_ld(&(bar)[XB_TMO])) break; if (_sp > XB_SPIN_CAP) { atomicAdd(&(bar)[XB_TMO], 1u); break; } } } } while (0)
; __device__ __forceinline__ void xcd_barrier(const XcdBarrier& b) {
;     ...
;         } else {
;             XB_SPIN(xb_ld(&bar[XB_XGEN(b.x)]) == gen, bar);
.LBB0_422:
	s_and_b32 s18, s11, 0xff
	s_cmp_lg_u32 s18, 0
	s_mov_b64 s[42:43], -1
	s_nop 0
	s_cbranch_scc0 .LBB0_425
	s_mov_b64 s[58:59], -1
	s_and_b64 vcc, exec, s[42:43]
	s_cbranch_vccz .LBB0_421

; __device__ __forceinline__ unsigned xb_ld(unsigned* p)              { return __hip_atomic_load(p, __ATOMIC_RELAXED, __HIP_MEMORY_SCOPE_AGENT); }
; __device__ __forceinline__ void xcd_barrier_complete(unsigned* bar, unsigned x, unsigned& nloc, unsigned& nx) {
;     ...
;     for (;;) {
;         sum = 0u; cnt = 0u; mine = 0u;
; #pragma unroll
;         for (unsigned j = 0; j < 16; ++j) { const unsigned c = xb_ld(&bar[XB_XCNT(j)]); sum += c; cnt += (c > 0u) ? 1u : 0u; mine = (j == x) ? c : mine; }
;         if (sum == G) break;
;         __builtin_amdgcn_s_sleep(1);
;         if ((++sp & 255u) == 0u) { if (xb_ld(&bar[XB_TMO])) break; if (sp > XB_SPIN_CAP) { atomicAdd(&bar[XB_TMO], 1u); break; } }
;     }
.LBB0_514:
	global_load_dword v15, v16, s[20:21] sc1
	global_load_dword v0, v16, s[22:23] sc1
	global_load_dword v1, v16, s[24:25] sc1
	global_load_dword v2, v16, s[26:27] sc1
	global_load_dword v3, v16, s[40:41] sc1
	global_load_dword v4, v16, s[42:43] sc1
	global_load_dword v5, v16, s[56:57] sc1
	global_load_dword v6, v16, s[58:59] sc1
	global_load_dword v7, v16, s[60:61] sc1
	global_load_dword v8, v16, s[62:63] sc1
	global_load_dword v9, v16, s[64:65] sc1
	global_load_dword v10, v16, s[66:67] sc1
	global_load_dword v11, v16, s[68:69] sc1
	global_load_dword v12, v16, s[70:71] sc1
	global_load_dword v13, v16, s[72:73] sc1
	global_load_dword v14, v16, s[74:75] sc1
	s_mov_b64 s[76:77], -1
	s_mov_b64 s[78:79], -1
	s_waitcnt vmcnt(14)
	v_add_u32_e32 v17, v0, v15
	s_waitcnt vmcnt(13)
	v_add_u32_e32 v17, v17, v1
	s_waitcnt vmcnt(12)
	v_add_u32_e32 v17, v17, v2
	s_waitcnt vmcnt(11)
	v_add_u32_e32 v17, v17, v3
	s_waitcnt vmcnt(10)
	v_add_u32_e32 v17, v17, v4
	s_waitcnt vmcnt(9)
	v_add_u32_e32 v17, v17, v5
	s_waitcnt vmcnt(8)
	v_add_u32_e32 v17, v17, v6
	s_waitcnt vmcnt(7)
	v_add_u32_e32 v17, v17, v7
	s_waitcnt vmcnt(6)
	v_add_u32_e32 v17, v17, v8
	s_waitcnt vmcnt(5)
	v_add_u32_e32 v17, v17, v9
	s_waitcnt vmcnt(4)
	v_add_u32_e32 v17, v17, v10
	s_waitcnt vmcnt(3)
	v_add_u32_e32 v17, v17, v11
	s_waitcnt vmcnt(2)
	v_add_u32_e32 v17, v17, v12
	s_waitcnt vmcnt(1)
	v_add_u32_e32 v17, v17, v13
	s_waitcnt vmcnt(0)
	v_add_u32_e32 v17, v17, v14
	v_cmp_eq_u32_e32 vcc, s11, v17
	s_cbranch_vccnz .LBB0_513
	s_and_b32 s18, s44, 0xff
	s_cmp_eq_u32 s18, 0
	s_mov_b64 s[80:81], -1
	s_nop 0
	s_cbranch_scc1 .LBB0_518
	s_and_b64 vcc, exec, s[80:81]
	s_cbranch_vccz .LBB0_513

; __device__ __forceinline__ unsigned xb_ld(unsigned* p)              { return __hip_atomic_load(p, __ATOMIC_RELAXED, __HIP_MEMORY_SCOPE_AGENT); }
; __device__ __forceinline__ unsigned xb_add(unsigned* p, unsigned v) { return __hip_atomic_fetch_add(p, v, __ATOMIC_RELAXED, __HIP_MEMORY_SCOPE_AGENT); }
; #define XB_SPIN(cond, bar) do { unsigned _sp = 0; while (cond) { __builtin_amdgcn_s_sleep(1); \
;     if ((++_sp & 255u) == 0u) { if (xb_ld(&(bar)[XB_TMO])) break; if (_sp > XB_SPIN_CAP) { atomicAdd(&(bar)[XB_TMO], 1u); break; } } } } while (0)
; __device__ __forceinline__ void xcd_barrier(const XcdBarrier& b) {
;     ...
;             const unsigned og = xb_add(&bar[XB_TOP], 1u);
;             const unsigned tg = og / nx;
;             if (og + 1u == (tg + 1u) * nx) xb_add(&bar[XB_TOPGEN], 1u);
;             else XB_SPIN(xb_ld(&bar[XB_TOPGEN]) == tg, bar);
.LBB0_530:
	s_and_b32 s18, s11, 0xff
	s_mov_b64 s[56:57], -1
	s_cmp_lg_u32 s18, 0
	s_mov_b64 s[60:61], -1
	s_nop 0
	s_cbranch_scc0 .LBB0_533
	s_and_b64 vcc, exec, s[60:61]
	s_cbranch_vccz .LBB0_529

; __device__ __forceinline__ unsigned xb_ld(unsigned* p)              { return __hip_atomic_load(p, __ATOMIC_RELAXED, __HIP_MEMORY_SCOPE_AGENT); }
; #define XB_SPIN(cond, bar) do { unsigned _sp = 0; while (cond) { __builtin_amdgcn_s_sleep(1); \
;     if ((++_sp & 255u) == 0u) { if (xb_ld(&(bar)[XB_TMO])) break; if (_sp > XB_SPIN_CAP) { atomicAdd(&(bar)[XB_TMO], 1u); break; } } } } while (0)
; __device__ __forceinline__ void xcd_barrier(const XcdBarrier& b) {
;     ...
;         } else {
;             XB_SPIN(xb_ld(&bar[XB_XGEN(b.x)]) == gen, bar);
.LBB0_547:
	s_and_b32 s18, s11, 0xff
	s_cmp_lg_u32 s18, 0
	s_mov_b64 s[58:59], -1
	s_nop 0
	s_cbranch_scc0 .LBB0_550
	s_mov_b64 s[60:61], -1
	s_and_b64 vcc, exec, s[58:59]
	s_cbranch_vccz .LBB0_546

; __device__ __forceinline__ unsigned xb_ld(unsigned* p)              { return __hip_atomic_load(p, __ATOMIC_RELAXED, __HIP_MEMORY_SCOPE_AGENT); }
; __device__ __forceinline__ void xcd_barrier_complete(unsigned* bar, unsigned x, unsigned& nloc, unsigned& nx) {
;     ...
;     for (;;) {
;         sum = 0u; cnt = 0u; mine = 0u;
; #pragma unroll
;         for (unsigned j = 0; j < 16; ++j) { const unsigned c = xb_ld(&bar[XB_XCNT(j)]); sum += c; cnt += (c > 0u) ? 1u : 0u; mine = (j == x) ? c : mine; }
;         if (sum == G) break;
;         __builtin_amdgcn_s_sleep(1);
;         if ((++sp & 255u) == 0u) { if (xb_ld(&bar[XB_TMO])) break; if (sp > XB_SPIN_CAP) { atomicAdd(&bar[XB_TMO], 1u); break; } }
;     }
.LBB0_780:
	global_load_dword v15, v16, s[22:23] sc1
	global_load_dword v0, v16, s[24:25] sc1
	global_load_dword v1, v16, s[26:27] sc1
	global_load_dword v2, v16, s[38:39] sc1
	global_load_dword v3, v16, s[40:41] sc1
	global_load_dword v4, v16, s[42:43] sc1
	global_load_dword v5, v16, s[56:57] sc1
	global_load_dword v6, v16, s[58:59] sc1
	global_load_dword v7, v16, s[60:61] sc1
	global_load_dword v8, v16, s[62:63] sc1
	global_load_dword v9, v16, s[64:65] sc1
	global_load_dword v10, v16, s[66:67] sc1
	global_load_dword v11, v16, s[68:69] sc1
	global_load_dword v12, v16, s[70:71] sc1
	global_load_dword v13, v16, s[72:73] sc1
	global_load_dword v14, v16, s[74:75] sc1
	s_mov_b64 s[76:77], -1
	s_mov_b64 s[78:79], -1
	s_waitcnt vmcnt(14)
	v_add_u32_e32 v17, v0, v15
	s_waitcnt vmcnt(13)
	v_add_u32_e32 v17, v17, v1
	s_waitcnt vmcnt(12)
	v_add_u32_e32 v17, v17, v2
	s_waitcnt vmcnt(11)
	v_add_u32_e32 v17, v17, v3
	s_waitcnt vmcnt(10)
	v_add_u32_e32 v17, v17, v4
	s_waitcnt vmcnt(9)
	v_add_u32_e32 v17, v17, v5
	s_waitcnt vmcnt(8)
	v_add_u32_e32 v17, v17, v6
	s_waitcnt vmcnt(7)
	v_add_u32_e32 v17, v17, v7
	s_waitcnt vmcnt(6)
	v_add_u32_e32 v17, v17, v8
	s_waitcnt vmcnt(5)
	v_add_u32_e32 v17, v17, v9
	s_waitcnt vmcnt(4)
	v_add_u32_e32 v17, v17, v10
	s_waitcnt vmcnt(3)
	v_add_u32_e32 v17, v17, v11
	s_waitcnt vmcnt(2)
	v_add_u32_e32 v17, v17, v12
	s_waitcnt vmcnt(1)
	v_add_u32_e32 v17, v17, v13
	s_waitcnt vmcnt(0)
	v_add_u32_e32 v17, v17, v14
	v_cmp_eq_u32_e32 vcc, s11, v17
	s_cbranch_vccnz .LBB0_779
	s_and_b32 s18, s44, 0xff
	s_cmp_eq_u32 s18, 0
	s_mov_b64 s[80:81], -1
	s_nop 0
	s_cbranch_scc1 .LBB0_784
	s_and_b64 vcc, exec, s[80:81]
	s_cbranch_vccz .LBB0_779

; __device__ __forceinline__ unsigned xb_ld(unsigned* p)              { return __hip_atomic_load(p, __ATOMIC_RELAXED, __HIP_MEMORY_SCOPE_AGENT); }
; __device__ __forceinline__ void xcd_barrier_complete(unsigned* bar, unsigned x, unsigned& nloc, unsigned& nx) {
;     ...
;     for (;;) {
;         sum = 0u; cnt = 0u; mine = 0u;
; #pragma unroll
;         for (unsigned j = 0; j < 16; ++j) { const unsigned c = xb_ld(&bar[XB_XCNT(j)]); sum += c; cnt += (c > 0u) ? 1u : 0u; mine = (j == x) ? c : mine; }
;         if (sum == G) break;
;         __builtin_amdgcn_s_sleep(1);
;         if ((++sp & 255u) == 0u) { if (xb_ld(&bar[XB_TMO])) break; if (sp > XB_SPIN_CAP) { atomicAdd(&bar[XB_TMO], 1u); break; } }
;     }
.LBB0_873:
	global_load_dword v15, v16, s[20:21] sc1
	global_load_dword v0, v16, s[22:23] sc1
	global_load_dword v1, v16, s[24:25] sc1
	global_load_dword v2, v16, s[26:27] sc1
	global_load_dword v3, v16, s[38:39] sc1
	global_load_dword v4, v16, s[40:41] sc1
	global_load_dword v5, v16, s[42:43] sc1
	global_load_dword v6, v16, s[54:55] sc1
	global_load_dword v7, v16, s[56:57] sc1
	global_load_dword v8, v16, s[58:59] sc1
	global_load_dword v9, v16, s[60:61] sc1
	global_load_dword v10, v16, s[62:63] sc1
	global_load_dword v11, v16, s[64:65] sc1
	global_load_dword v12, v16, s[66:67] sc1
	global_load_dword v13, v16, s[68:69] sc1
	global_load_dword v14, v16, s[70:71] sc1
	s_mov_b64 s[72:73], -1
	s_mov_b64 s[74:75], -1
	s_waitcnt vmcnt(14)
	v_add_u32_e32 v17, v0, v15
	s_waitcnt vmcnt(13)
	v_add_u32_e32 v17, v17, v1
	s_waitcnt vmcnt(12)
	v_add_u32_e32 v17, v17, v2
	s_waitcnt vmcnt(11)
	v_add_u32_e32 v17, v17, v3
	s_waitcnt vmcnt(10)
	v_add_u32_e32 v17, v17, v4
	s_waitcnt vmcnt(9)
	v_add_u32_e32 v17, v17, v5
	s_waitcnt vmcnt(8)
	v_add_u32_e32 v17, v17, v6
	s_waitcnt vmcnt(7)
	v_add_u32_e32 v17, v17, v7
	s_waitcnt vmcnt(6)
	v_add_u32_e32 v17, v17, v8
	s_waitcnt vmcnt(5)
	v_add_u32_e32 v17, v17, v9
	s_waitcnt vmcnt(4)
	v_add_u32_e32 v17, v17, v10
	s_waitcnt vmcnt(3)
	v_add_u32_e32 v17, v17, v11
	s_waitcnt vmcnt(2)
	v_add_u32_e32 v17, v17, v12
	s_waitcnt vmcnt(1)
	v_add_u32_e32 v17, v17, v13
	s_waitcnt vmcnt(0)
	v_add_u32_e32 v17, v17, v14
	v_cmp_eq_u32_e32 vcc, s11, v17
	s_cbranch_vccnz .LBB0_872
	s_and_b32 s18, s44, 0xff
	s_cmp_eq_u32 s18, 0
	s_mov_b64 s[76:77], -1
	s_nop 0
	s_cbranch_scc1 .LBB0_877
	s_and_b64 vcc, exec, s[76:77]
	s_cbranch_vccz .LBB0_872

; __device__ __forceinline__ unsigned xb_ld(unsigned* p)              { return __hip_atomic_load(p, __ATOMIC_RELAXED, __HIP_MEMORY_SCOPE_AGENT); }
; __device__ __forceinline__ unsigned xb_add(unsigned* p, unsigned v) { return __hip_atomic_fetch_add(p, v, __ATOMIC_RELAXED, __HIP_MEMORY_SCOPE_AGENT); }
; #define XB_SPIN(cond, bar) do { unsigned _sp = 0; while (cond) { __builtin_amdgcn_s_sleep(1); \
;     if ((++_sp & 255u) == 0u) { if (xb_ld(&(bar)[XB_TMO])) break; if (_sp > XB_SPIN_CAP) { atomicAdd(&(bar)[XB_TMO], 1u); break; } } } } while (0)
; __device__ __forceinline__ void xcd_barrier(const XcdBarrier& b) {
;     ...
;             const unsigned og = xb_add(&bar[XB_TOP], 1u);
;             const unsigned tg = og / nx;
;             if (og + 1u == (tg + 1u) * nx) xb_add(&bar[XB_TOPGEN], 1u);
;             else XB_SPIN(xb_ld(&bar[XB_TOPGEN]) == tg, bar);
.LBB0_889:
	s_and_b32 s18, s11, 0xff
	s_mov_b64 s[42:43], -1
	s_cmp_lg_u32 s18, 0
	s_mov_b64 s[56:57], -1
	s_nop 0
	s_cbranch_scc0 .LBB0_892
	s_and_b64 vcc, exec, s[56:57]
	s_cbranch_vccz .LBB0_888

; __device__ __forceinline__ unsigned xb_ld(unsigned* p)              { return __hip_atomic_load(p, __ATOMIC_RELAXED, __HIP_MEMORY_SCOPE_AGENT); }
; #define XB_SPIN(cond, bar) do { unsigned _sp = 0; while (cond) { __builtin_amdgcn_s_sleep(1); \
;     if ((++_sp & 255u) == 0u) { if (xb_ld(&(bar)[XB_TMO])) break; if (_sp > XB_SPIN_CAP) { atomicAdd(&(bar)[XB_TMO], 1u); break; } } } } while (0)
; __device__ __forceinline__ void xcd_barrier(const XcdBarrier& b) {
;     ...
;         } else {
;             XB_SPIN(xb_ld(&bar[XB_XGEN(b.x)]) == gen, bar);
.LBB0_906:
	s_and_b32 s18, s11, 0xff
	s_cmp_lg_u32 s18, 0
	s_mov_b64 s[54:55], -1
	s_nop 0
	s_cbranch_scc0 .LBB0_909
	s_mov_b64 s[56:57], -1
	s_and_b64 vcc, exec, s[54:55]
	s_cbranch_vccz .LBB0_905

; __device__ __forceinline__ unsigned xb_ld(unsigned* p)              { return __hip_atomic_load(p, __ATOMIC_RELAXED, __HIP_MEMORY_SCOPE_AGENT); }
; __device__ __forceinline__ void xcd_barrier_complete(unsigned* bar, unsigned x, unsigned& nloc, unsigned& nx) {
;     ...
;     for (;;) {
;         sum = 0u; cnt = 0u; mine = 0u;
; #pragma unroll
;         for (unsigned j = 0; j < 16; ++j) { const unsigned c = xb_ld(&bar[XB_XCNT(j)]); sum += c; cnt += (c > 0u) ? 1u : 0u; mine = (j == x) ? c : mine; }
;         if (sum == G) break;
;         __builtin_amdgcn_s_sleep(1);
;         if ((++sp & 255u) == 0u) { if (xb_ld(&bar[XB_TMO])) break; if (sp > XB_SPIN_CAP) { atomicAdd(&bar[XB_TMO], 1u); break; } }
;     }
.LBB0_999:
	global_load_dword v15, v16, s[6:7] sc1
	global_load_dword v0, v16, s[20:21] sc1
	global_load_dword v1, v16, s[22:23] sc1
	global_load_dword v2, v16, s[24:25] sc1
	global_load_dword v3, v16, s[26:27] sc1
	global_load_dword v4, v16, s[30:31] sc1
	global_load_dword v5, v16, s[38:39] sc1
	global_load_dword v6, v16, s[40:41] sc1
	global_load_dword v7, v16, s[42:43] sc1
	global_load_dword v8, v16, s[52:53] sc1
	global_load_dword v9, v16, s[54:55] sc1
	global_load_dword v10, v16, s[56:57] sc1
	global_load_dword v11, v16, s[58:59] sc1
	global_load_dword v12, v16, s[60:61] sc1
	global_load_dword v13, v16, s[62:63] sc1
	global_load_dword v14, v16, s[64:65] sc1
	s_mov_b64 s[66:67], -1
	s_mov_b64 s[68:69], -1
	s_waitcnt vmcnt(14)
	v_add_u32_e32 v17, v0, v15
	s_waitcnt vmcnt(13)
	v_add_u32_e32 v17, v17, v1
	s_waitcnt vmcnt(12)
	v_add_u32_e32 v17, v17, v2
	s_waitcnt vmcnt(11)
	v_add_u32_e32 v17, v17, v3
	s_waitcnt vmcnt(10)
	v_add_u32_e32 v17, v17, v4
	s_waitcnt vmcnt(9)
	v_add_u32_e32 v17, v17, v5
	s_waitcnt vmcnt(8)
	v_add_u32_e32 v17, v17, v6
	s_waitcnt vmcnt(7)
	v_add_u32_e32 v17, v17, v7
	s_waitcnt vmcnt(6)
	v_add_u32_e32 v17, v17, v8
	s_waitcnt vmcnt(5)
	v_add_u32_e32 v17, v17, v9
	s_waitcnt vmcnt(4)
	v_add_u32_e32 v17, v17, v10
	s_waitcnt vmcnt(3)
	v_add_u32_e32 v17, v17, v11
	s_waitcnt vmcnt(2)
	v_add_u32_e32 v17, v17, v12
	s_waitcnt vmcnt(1)
	v_add_u32_e32 v17, v17, v13
	s_waitcnt vmcnt(0)
	v_add_u32_e32 v17, v17, v14
	v_cmp_eq_u32_e32 vcc, s11, v17
	s_cbranch_vccnz .LBB0_998
	s_and_b32 s18, s44, 0xff
	s_cmp_eq_u32 s18, 0
	s_mov_b64 s[70:71], -1
	s_nop 0
	s_cbranch_scc1 .LBB0_1003
	s_and_b64 vcc, exec, s[70:71]
	s_cbranch_vccz .LBB0_998

; __device__ __forceinline__ unsigned xb_ld(unsigned* p)              { return __hip_atomic_load(p, __ATOMIC_RELAXED, __HIP_MEMORY_SCOPE_AGENT); }
; __device__ __forceinline__ unsigned xb_add(unsigned* p, unsigned v) { return __hip_atomic_fetch_add(p, v, __ATOMIC_RELAXED, __HIP_MEMORY_SCOPE_AGENT); }
; #define XB_SPIN(cond, bar) do { unsigned _sp = 0; while (cond) { __builtin_amdgcn_s_sleep(1); \
;     if ((++_sp & 255u) == 0u) { if (xb_ld(&(bar)[XB_TMO])) break; if (_sp > XB_SPIN_CAP) { atomicAdd(&(bar)[XB_TMO], 1u); break; } } } } while (0)
; __device__ __forceinline__ void xcd_barrier(const XcdBarrier& b) {
;     ...
;             const unsigned og = xb_add(&bar[XB_TOP], 1u);
;             const unsigned tg = og / nx;
;             if (og + 1u == (tg + 1u) * nx) xb_add(&bar[XB_TOPGEN], 1u);
;             else XB_SPIN(xb_ld(&bar[XB_TOPGEN]) == tg, bar);
.LBB0_1015:
	s_and_b32 s18, s11, 0xff
	s_mov_b64 s[38:39], -1
	s_cmp_lg_u32 s18, 0
	s_mov_b64 s[42:43], -1
	s_nop 0
	s_cbranch_scc0 .LBB0_1018
	s_and_b64 vcc, exec, s[42:43]
	s_cbranch_vccz .LBB0_1014

; __device__ __forceinline__ unsigned xb_ld(unsigned* p)              { return __hip_atomic_load(p, __ATOMIC_RELAXED, __HIP_MEMORY_SCOPE_AGENT); }
; #define XB_SPIN(cond, bar) do { unsigned _sp = 0; while (cond) { __builtin_amdgcn_s_sleep(1); \
;     if ((++_sp & 255u) == 0u) { if (xb_ld(&(bar)[XB_TMO])) break; if (_sp > XB_SPIN_CAP) { atomicAdd(&(bar)[XB_TMO], 1u); break; } } } } while (0)
; __device__ __forceinline__ void xcd_barrier(const XcdBarrier& b) {
;     ...
;         } else {
;             XB_SPIN(xb_ld(&bar[XB_XGEN(b.x)]) == gen, bar);
.LBB0_1032:
	s_and_b32 s18, s11, 0xff
	s_cmp_lg_u32 s18, 0
	s_mov_b64 s[40:41], -1
	s_nop 0
	s_cbranch_scc0 .LBB0_1035
	s_mov_b64 s[42:43], -1
	s_and_b64 vcc, exec, s[40:41]
	s_cbranch_vccz .LBB0_1031

; __device__ __forceinline__ unsigned xb_ld(unsigned* p)              { return __hip_atomic_load(p, __ATOMIC_RELAXED, __HIP_MEMORY_SCOPE_AGENT); }
; __device__ __forceinline__ void xcd_barrier_complete(unsigned* bar, unsigned x, unsigned& nloc, unsigned& nx) {
;     ...
;     for (;;) {
;         sum = 0u; cnt = 0u; mine = 0u;
; #pragma unroll
;         for (unsigned j = 0; j < 16; ++j) { const unsigned c = xb_ld(&bar[XB_XCNT(j)]); sum += c; cnt += (c > 0u) ? 1u : 0u; mine = (j == x) ? c : mine; }
;         if (sum == G) break;
;         __builtin_amdgcn_s_sleep(1);
;         if ((++sp & 255u) == 0u) { if (xb_ld(&bar[XB_TMO])) break; if (sp > XB_SPIN_CAP) { atomicAdd(&bar[XB_TMO], 1u); break; } }
;     }
.LBB0_1093:
	global_load_dword v15, v16, s[20:21] sc1
	global_load_dword v0, v16, s[22:23] sc1
	global_load_dword v1, v16, s[24:25] sc1
	global_load_dword v2, v16, s[26:27] sc1
	global_load_dword v3, v16, s[30:31] sc1
	global_load_dword v4, v16, s[36:37] sc1
	global_load_dword v5, v16, s[38:39] sc1
	global_load_dword v6, v16, s[40:41] sc1
	global_load_dword v7, v16, s[42:43] sc1
	global_load_dword v8, v16, s[52:53] sc1
	global_load_dword v9, v16, s[54:55] sc1
	global_load_dword v10, v16, s[56:57] sc1
	global_load_dword v11, v16, s[58:59] sc1
	global_load_dword v12, v16, s[60:61] sc1
	global_load_dword v13, v16, s[62:63] sc1
	global_load_dword v14, v16, s[64:65] sc1
	s_mov_b64 s[66:67], -1
	s_mov_b64 s[68:69], -1
	s_waitcnt vmcnt(14)
	v_add_u32_e32 v17, v0, v15
	s_waitcnt vmcnt(13)
	v_add_u32_e32 v17, v17, v1
	s_waitcnt vmcnt(12)
	v_add_u32_e32 v17, v17, v2
	s_waitcnt vmcnt(11)
	v_add_u32_e32 v17, v17, v3
	s_waitcnt vmcnt(10)
	v_add_u32_e32 v17, v17, v4
	s_waitcnt vmcnt(9)
	v_add_u32_e32 v17, v17, v5
	s_waitcnt vmcnt(8)
	v_add_u32_e32 v17, v17, v6
	s_waitcnt vmcnt(7)
	v_add_u32_e32 v17, v17, v7
	s_waitcnt vmcnt(6)
	v_add_u32_e32 v17, v17, v8
	s_waitcnt vmcnt(5)
	v_add_u32_e32 v17, v17, v9
	s_waitcnt vmcnt(4)
	v_add_u32_e32 v17, v17, v10
	s_waitcnt vmcnt(3)
	v_add_u32_e32 v17, v17, v11
	s_waitcnt vmcnt(2)
	v_add_u32_e32 v17, v17, v12
	s_waitcnt vmcnt(1)
	v_add_u32_e32 v17, v17, v13
	s_waitcnt vmcnt(0)
	v_add_u32_e32 v17, v17, v14
	v_cmp_eq_u32_e32 vcc, s11, v17
	s_cbranch_vccnz .LBB0_1092
	s_and_b32 s18, s44, 0xff
	s_cmp_eq_u32 s18, 0
	s_mov_b64 s[70:71], -1
	s_nop 0
	s_cbranch_scc1 .LBB0_1097
	s_and_b64 vcc, exec, s[70:71]
	s_cbranch_vccz .LBB0_1092

; __device__ __forceinline__ unsigned xb_ld(unsigned* p)              { return __hip_atomic_load(p, __ATOMIC_RELAXED, __HIP_MEMORY_SCOPE_AGENT); }
; __device__ __forceinline__ void xcd_barrier_complete(unsigned* bar, unsigned x, unsigned& nloc, unsigned& nx) {
;     ...
;     for (;;) {
;         sum = 0u; cnt = 0u; mine = 0u;
; #pragma unroll
;         for (unsigned j = 0; j < 16; ++j) { const unsigned c = xb_ld(&bar[XB_XCNT(j)]); sum += c; cnt += (c > 0u) ? 1u : 0u; mine = (j == x) ? c : mine; }
;         if (sum == G) break;
;         __builtin_amdgcn_s_sleep(1);
;         if ((++sp & 255u) == 0u) { if (xb_ld(&bar[XB_TMO])) break; if (sp > XB_SPIN_CAP) { atomicAdd(&bar[XB_TMO], 1u); break; } }
;     }
.LBB0_1168:
	global_load_dword v15, v16, s[8:9] sc1
	global_load_dword v0, v16, s[20:21] sc1
	global_load_dword v1, v16, s[22:23] sc1
	global_load_dword v2, v16, s[24:25] sc1
	global_load_dword v3, v16, s[26:27] sc1
	global_load_dword v4, v16, s[30:31] sc1
	global_load_dword v5, v16, s[36:37] sc1
	global_load_dword v6, v16, s[38:39] sc1
	global_load_dword v7, v16, s[40:41] sc1
	global_load_dword v8, v16, s[42:43] sc1
	global_load_dword v9, v16, s[52:53] sc1
	global_load_dword v10, v16, s[54:55] sc1
	global_load_dword v11, v16, s[56:57] sc1
	global_load_dword v12, v16, s[58:59] sc1
	global_load_dword v13, v16, s[60:61] sc1
	global_load_dword v14, v16, s[62:63] sc1
	s_mov_b64 s[64:65], -1
	s_mov_b64 s[66:67], -1
	s_waitcnt vmcnt(14)
	v_add_u32_e32 v17, v0, v15
	s_waitcnt vmcnt(13)
	v_add_u32_e32 v17, v17, v1
	s_waitcnt vmcnt(12)
	v_add_u32_e32 v17, v17, v2
	s_waitcnt vmcnt(11)
	v_add_u32_e32 v17, v17, v3
	s_waitcnt vmcnt(10)
	v_add_u32_e32 v17, v17, v4
	s_waitcnt vmcnt(9)
	v_add_u32_e32 v17, v17, v5
	s_waitcnt vmcnt(8)
	v_add_u32_e32 v17, v17, v6
	s_waitcnt vmcnt(7)
	v_add_u32_e32 v17, v17, v7
	s_waitcnt vmcnt(6)
	v_add_u32_e32 v17, v17, v8
	s_waitcnt vmcnt(5)
	v_add_u32_e32 v17, v17, v9
	s_waitcnt vmcnt(4)
	v_add_u32_e32 v17, v17, v10
	s_waitcnt vmcnt(3)
	v_add_u32_e32 v17, v17, v11
	s_waitcnt vmcnt(2)
	v_add_u32_e32 v17, v17, v12
	s_waitcnt vmcnt(1)
	v_add_u32_e32 v17, v17, v13
	s_waitcnt vmcnt(0)
	v_add_u32_e32 v17, v17, v14
	v_cmp_eq_u32_e32 vcc, s11, v17
	s_cbranch_vccnz .LBB0_1167
	s_and_b32 s18, s44, 0xff
	s_cmp_eq_u32 s18, 0
	s_mov_b64 s[68:69], -1
	s_nop 0
	s_cbranch_scc1 .LBB0_1172
	s_and_b64 vcc, exec, s[68:69]
	s_cbranch_vccz .LBB0_1167

; __device__ __forceinline__ unsigned xb_ld(unsigned* p)              { return __hip_atomic_load(p, __ATOMIC_RELAXED, __HIP_MEMORY_SCOPE_AGENT); }
; __device__ __forceinline__ void xcd_barrier_complete(unsigned* bar, unsigned x, unsigned& nloc, unsigned& nx) {
;     ...
;     for (;;) {
;         sum = 0u; cnt = 0u; mine = 0u;
; #pragma unroll
;         for (unsigned j = 0; j < 16; ++j) { const unsigned c = xb_ld(&bar[XB_XCNT(j)]); sum += c; cnt += (c > 0u) ? 1u : 0u; mine = (j == x) ? c : mine; }
;         if (sum == G) break;
;         __builtin_amdgcn_s_sleep(1);
;         if ((++sp & 255u) == 0u) { if (xb_ld(&bar[XB_TMO])) break; if (sp > XB_SPIN_CAP) { atomicAdd(&bar[XB_TMO], 1u); break; } }
;     }
.LBB0_1324:
	global_load_dword v15, v16, s[8:9] sc1
	global_load_dword v0, v16, s[18:19] sc1
	global_load_dword v1, v16, s[20:21] sc1
	global_load_dword v2, v16, s[22:23] sc1
	global_load_dword v3, v16, s[24:25] sc1
	global_load_dword v4, v16, s[26:27] sc1
	global_load_dword v5, v16, s[28:29] sc1
	global_load_dword v6, v16, s[30:31] sc1
	global_load_dword v7, v16, s[36:37] sc1
	global_load_dword v8, v16, s[38:39] sc1
	global_load_dword v9, v16, s[40:41] sc1
	global_load_dword v10, v16, s[42:43] sc1
	global_load_dword v11, v16, s[46:47] sc1
	global_load_dword v12, v16, s[48:49] sc1
	global_load_dword v13, v16, s[50:51] sc1
	global_load_dword v14, v16, s[52:53] sc1
	s_mov_b64 s[54:55], -1
	s_mov_b64 s[56:57], -1
	s_waitcnt vmcnt(14)
	v_add_u32_e32 v17, v0, v15
	s_waitcnt vmcnt(13)
	v_add_u32_e32 v17, v17, v1
	s_waitcnt vmcnt(12)
	v_add_u32_e32 v17, v17, v2
	s_waitcnt vmcnt(11)
	v_add_u32_e32 v17, v17, v3
	s_waitcnt vmcnt(10)
	v_add_u32_e32 v17, v17, v4
	s_waitcnt vmcnt(9)
	v_add_u32_e32 v17, v17, v5
	s_waitcnt vmcnt(8)
	v_add_u32_e32 v17, v17, v6
	s_waitcnt vmcnt(7)
	v_add_u32_e32 v17, v17, v7
	s_waitcnt vmcnt(6)
	v_add_u32_e32 v17, v17, v8
	s_waitcnt vmcnt(5)
	v_add_u32_e32 v17, v17, v9
	s_waitcnt vmcnt(4)
	v_add_u32_e32 v17, v17, v10
	s_waitcnt vmcnt(3)
	v_add_u32_e32 v17, v17, v11
	s_waitcnt vmcnt(2)
	v_add_u32_e32 v17, v17, v12
	s_waitcnt vmcnt(1)
	v_add_u32_e32 v17, v17, v13
	s_waitcnt vmcnt(0)
	v_add_u32_e32 v17, v17, v14
	v_cmp_eq_u32_e32 vcc, s11, v17
	s_cbranch_vccnz .LBB0_1323
	s_and_b32 s33, s35, 0xff
	s_cmp_eq_u32 s33, 0
	s_mov_b64 s[58:59], -1
	s_nop 0
	s_cbranch_scc1 .LBB0_1328
	s_and_b64 vcc, exec, s[58:59]
	s_cbranch_vccz .LBB0_1323

; __device__ __forceinline__ unsigned xb_ld(unsigned* p)              { return __hip_atomic_load(p, __ATOMIC_RELAXED, __HIP_MEMORY_SCOPE_AGENT); }
; __device__ __forceinline__ unsigned xb_add(unsigned* p, unsigned v) { return __hip_atomic_fetch_add(p, v, __ATOMIC_RELAXED, __HIP_MEMORY_SCOPE_AGENT); }
; #define XB_SPIN(cond, bar) do { unsigned _sp = 0; while (cond) { __builtin_amdgcn_s_sleep(1); \
;     if ((++_sp & 255u) == 0u) { if (xb_ld(&(bar)[XB_TMO])) break; if (_sp > XB_SPIN_CAP) { atomicAdd(&(bar)[XB_TMO], 1u); break; } } } } while (0)
; __device__ __forceinline__ void xcd_barrier(const XcdBarrier& b) {
;     ...
;             const unsigned og = xb_add(&bar[XB_TOP], 1u);
;             const unsigned tg = og / nx;
;             if (og + 1u == (tg + 1u) * nx) xb_add(&bar[XB_TOPGEN], 1u);
;             else XB_SPIN(xb_ld(&bar[XB_TOPGEN]) == tg, bar);
.LBB0_1340:
	s_and_b32 s30, s11, 0xff
	s_mov_b64 s[28:29], -1
	s_cmp_lg_u32 s30, 0
	s_mov_b64 s[36:37], -1
	s_nop 0
	s_cbranch_scc0 .LBB0_1343
	s_and_b64 vcc, exec, s[36:37]
	s_cbranch_vccz .LBB0_1339

; __device__ __forceinline__ unsigned xb_ld(unsigned* p)              { return __hip_atomic_load(p, __ATOMIC_RELAXED, __HIP_MEMORY_SCOPE_AGENT); }
; #define XB_SPIN(cond, bar) do { unsigned _sp = 0; while (cond) { __builtin_amdgcn_s_sleep(1); \
;     if ((++_sp & 255u) == 0u) { if (xb_ld(&(bar)[XB_TMO])) break; if (_sp > XB_SPIN_CAP) { atomicAdd(&(bar)[XB_TMO], 1u); break; } } } } while (0)
; __device__ __forceinline__ void xcd_barrier(const XcdBarrier& b) {
;     ...
;         } else {
;             XB_SPIN(xb_ld(&bar[XB_XGEN(b.x)]) == gen, bar);
.LBB0_1357:
	s_and_b32 s28, s11, 0xff
	s_cmp_lg_u32 s28, 0
	s_mov_b64 s[30:31], -1
	s_nop 0
	s_cbranch_scc0 .LBB0_1360
	s_mov_b64 s[36:37], -1
	s_and_b64 vcc, exec, s[30:31]
	s_cbranch_vccz .LBB0_1356
